# S1 n-tile loop: pairs of tiles exchanged with v_permlane16_swap, 16 dwordx4 stores per wave instead of 32 dwordx2
# speedup vs baseline: 1.0327x; 1.0083x over previous
.LBB0_305:
	s_or_b64 exec, exec, s[4:5]
	s_waitcnt lgkmcnt(0)
	s_barrier
	ds_read_b64_tr_b16 v[0:1], v102 offset:2176
	ds_read_b128 v[78:81], v93
	ds_read_b128 v[58:61], v93 offset:16
	ds_read_b64_tr_b16 v[2:3], v102
	ds_read_b64_tr_b16 v[18:19], v102 offset:32
	s_waitcnt lgkmcnt(4)
	v_and_b32_e32 v7, 0xffff0000, v0
	v_lshlrev_b32_e32 v6, 16, v0
	s_waitcnt lgkmcnt(2)
	v_pk_mul_f32 v[6:7], v[58:59], v[6:7]
	s_waitcnt lgkmcnt(1)
	v_and_b32_e32 v5, 0xffff0000, v2
	v_lshlrev_b32_e32 v4, 16, v2
	v_and_b32_e32 v11, 0xffff0000, v3
	v_lshlrev_b32_e32 v10, 16, v3
	v_pk_mul_f32 v[4:5], v[78:79], v[4:5]
	v_pk_mul_f32 v[2:3], v[80:81], v[10:11]
	v_and_b32_e32 v11, 0xffff0000, v1
	v_lshlrev_b32_e32 v10, 16, v1
	v_cvt_pk_bf16_f32 v0, v4, v5
	v_cvt_pk_bf16_f32 v1, v2, v3
	v_cvt_pk_bf16_f32 v2, v6, v7
	ds_read_b64_tr_b16 v[4:5], v102 offset:17408
	ds_read_b64_tr_b16 v[6:7], v102 offset:19584
	ds_read_b128 v[74:77], v93 offset:128
	ds_read_b128 v[70:73], v93 offset:144
	v_pk_mul_f32 v[10:11], v[60:61], v[10:11]
	s_waitcnt lgkmcnt(3)
	v_and_b32_e32 v15, 0xffff0000, v5
	v_cvt_pk_bf16_f32 v3, v10, v11
	v_and_b32_e32 v11, 0xffff0000, v4
	v_lshlrev_b32_e32 v10, 16, v4
	s_waitcnt lgkmcnt(2)
	v_and_b32_e32 v13, 0xffff0000, v6
	v_lshlrev_b32_e32 v12, 16, v6
	s_waitcnt lgkmcnt(1)
	v_pk_mul_f32 v[10:11], v[74:75], v[10:11]
	s_waitcnt lgkmcnt(0)
	v_pk_mul_f32 v[12:13], v[70:71], v[12:13]
	v_lshlrev_b32_e32 v14, 16, v5
	v_and_b32_e32 v5, 0xffff0000, v7
	v_lshlrev_b32_e32 v4, 16, v7
	v_pk_mul_f32 v[16:17], v[72:73], v[4:5]
	v_cvt_pk_bf16_f32 v4, v10, v11
	v_cvt_pk_bf16_f32 v6, v12, v13
	ds_read_b64_tr_b16 v[10:11], v102 offset:34816
	ds_read_b64_tr_b16 v[12:13], v102 offset:36992
	ds_read_b128 v[66:69], v93 offset:256
	ds_read_b128 v[62:65], v93 offset:272
	v_pk_mul_f32 v[14:15], v[76:77], v[14:15]
	v_cvt_pk_bf16_f32 v7, v16, v17
	v_cvt_pk_bf16_f32 v5, v14, v15
	s_waitcnt lgkmcnt(3)
	v_and_b32_e32 v15, 0xffff0000, v10
	v_lshlrev_b32_e32 v14, 16, v10
	s_waitcnt lgkmcnt(2)
	v_and_b32_e32 v17, 0xffff0000, v12
	v_lshlrev_b32_e32 v16, 16, v12
	s_waitcnt lgkmcnt(1)
	v_pk_mul_f32 v[14:15], v[66:67], v[14:15]
	s_waitcnt lgkmcnt(0)
	v_pk_mul_f32 v[16:17], v[62:63], v[16:17]
	v_and_b32_e32 v21, 0xffff0000, v11
	v_lshlrev_b32_e32 v20, 16, v11
	v_and_b32_e32 v11, 0xffff0000, v13
	v_lshlrev_b32_e32 v10, 16, v13
	v_pk_mul_f32 v[22:23], v[64:65], v[10:11]
	v_cvt_pk_bf16_f32 v10, v14, v15
	v_cvt_pk_bf16_f32 v12, v16, v17
	ds_read_b64_tr_b16 v[14:15], v102 offset:52224
	ds_read_b64_tr_b16 v[16:17], v102 offset:54400
	ds_read_b128 v[38:41], v93 offset:384
	ds_read_b128 v[34:37], v93 offset:400
	v_pk_mul_f32 v[20:21], v[68:69], v[20:21]
	s_waitcnt lgkmcnt(3)
	v_and_b32_e32 v25, 0xffff0000, v15
	v_cvt_pk_bf16_f32 v11, v20, v21
	v_and_b32_e32 v21, 0xffff0000, v14
	v_lshlrev_b32_e32 v20, 16, v14
	s_waitcnt lgkmcnt(1)
	v_pk_mul_f32 v[20:21], v[38:39], v[20:21]
	v_lshlrev_b32_e32 v24, 16, v15
	v_and_b32_e32 v15, 0xffff0000, v17
	v_lshlrev_b32_e32 v14, 16, v17
	s_waitcnt lgkmcnt(0)
	v_pk_mul_f32 v[26:27], v[36:37], v[14:15]
	v_cvt_pk_bf16_f32 v14, v20, v21
	ds_read_b64_tr_b16 v[20:21], v102 offset:2208
	v_cvt_pk_bf16_f32 v13, v22, v23
	v_and_b32_e32 v23, 0xffff0000, v16
	v_lshlrev_b32_e32 v22, 16, v16
	v_pk_mul_f32 v[22:23], v[34:35], v[22:23]
	v_pk_mul_f32 v[24:25], v[40:41], v[24:25]
	v_cvt_pk_bf16_f32 v16, v22, v23
	v_cvt_pk_bf16_f32 v15, v24, v25
	v_and_b32_e32 v23, 0xffff0000, v18
	v_lshlrev_b32_e32 v22, 16, v18
	s_waitcnt lgkmcnt(0)
	v_and_b32_e32 v25, 0xffff0000, v20
	v_lshlrev_b32_e32 v24, 16, v20
	v_cvt_pk_bf16_f32 v17, v26, v27
	v_pk_mul_f32 v[22:23], v[78:79], v[22:23]
	v_pk_mul_f32 v[24:25], v[58:59], v[24:25]
	v_and_b32_e32 v27, 0xffff0000, v19
	v_lshlrev_b32_e32 v26, 16, v19
	v_and_b32_e32 v19, 0xffff0000, v21
	v_lshlrev_b32_e32 v18, 16, v21
	v_pk_mul_f32 v[28:29], v[60:61], v[18:19]
	v_cvt_pk_bf16_f32 v18, v22, v23
	v_cvt_pk_bf16_f32 v20, v24, v25
	ds_read_b64_tr_b16 v[22:23], v102 offset:17440
	ds_read_b64_tr_b16 v[24:25], v102 offset:19616
	v_pk_mul_f32 v[26:27], v[80:81], v[26:27]
	v_cvt_pk_bf16_f32 v21, v28, v29
	v_cvt_pk_bf16_f32 v19, v26, v27
	s_waitcnt lgkmcnt(1)
	v_and_b32_e32 v27, 0xffff0000, v22
	v_lshlrev_b32_e32 v26, 16, v22
	s_waitcnt lgkmcnt(0)
	v_and_b32_e32 v29, 0xffff0000, v24
	v_lshlrev_b32_e32 v28, 16, v24
	v_pk_mul_f32 v[26:27], v[74:75], v[26:27]
	v_pk_mul_f32 v[28:29], v[70:71], v[28:29]
	v_and_b32_e32 v31, 0xffff0000, v23
	v_lshlrev_b32_e32 v30, 16, v23
	v_and_b32_e32 v23, 0xffff0000, v25
	v_lshlrev_b32_e32 v22, 16, v25
	v_pk_mul_f32 v[32:33], v[72:73], v[22:23]
	v_cvt_pk_bf16_f32 v22, v26, v27
	v_cvt_pk_bf16_f32 v24, v28, v29
	ds_read_b64_tr_b16 v[26:27], v102 offset:34848
	ds_read_b64_tr_b16 v[28:29], v102 offset:37024
	v_pk_mul_f32 v[30:31], v[76:77], v[30:31]
	v_cvt_pk_bf16_f32 v25, v32, v33
	v_cvt_pk_bf16_f32 v23, v30, v31
	s_waitcnt lgkmcnt(1)
	v_and_b32_e32 v31, 0xffff0000, v26
	v_lshlrev_b32_e32 v30, 16, v26
	s_waitcnt lgkmcnt(0)
	v_and_b32_e32 v33, 0xffff0000, v28
	v_lshlrev_b32_e32 v32, 16, v28
	v_pk_mul_f32 v[30:31], v[66:67], v[30:31]
	v_pk_mul_f32 v[32:33], v[62:63], v[32:33]
	v_and_b32_e32 v43, 0xffff0000, v27
	v_lshlrev_b32_e32 v42, 16, v27
	v_and_b32_e32 v27, 0xffff0000, v29
	v_lshlrev_b32_e32 v26, 16, v29
	v_pk_mul_f32 v[44:45], v[64:65], v[26:27]
	v_cvt_pk_bf16_f32 v26, v30, v31
	v_cvt_pk_bf16_f32 v28, v32, v33
	ds_read_b64_tr_b16 v[30:31], v102 offset:52256
	ds_read_b64_tr_b16 v[32:33], v102 offset:54432
	v_pk_mul_f32 v[42:43], v[68:69], v[42:43]
	v_cvt_pk_bf16_f32 v29, v44, v45
	v_cvt_pk_bf16_f32 v27, v42, v43
	s_waitcnt lgkmcnt(1)
	v_and_b32_e32 v43, 0xffff0000, v30
	v_lshlrev_b32_e32 v42, 16, v30
	s_waitcnt lgkmcnt(0)
	v_and_b32_e32 v45, 0xffff0000, v32
	v_lshlrev_b32_e32 v44, 16, v32
	v_pk_mul_f32 v[42:43], v[38:39], v[42:43]
	v_pk_mul_f32 v[44:45], v[34:35], v[44:45]
	v_and_b32_e32 v47, 0xffff0000, v31
	v_lshlrev_b32_e32 v46, 16, v31
	v_and_b32_e32 v31, 0xffff0000, v33
	v_lshlrev_b32_e32 v30, 16, v33
	v_pk_mul_f32 v[48:49], v[36:37], v[30:31]
	v_cvt_pk_bf16_f32 v30, v42, v43
	v_cvt_pk_bf16_f32 v32, v44, v45
	ds_read_b64_tr_b16 v[42:43], v102 offset:64
	ds_read_b64_tr_b16 v[44:45], v102 offset:2240
	v_pk_mul_f32 v[46:47], v[40:41], v[46:47]
	v_cvt_pk_bf16_f32 v33, v48, v49
	v_cvt_pk_bf16_f32 v31, v46, v47
	s_waitcnt lgkmcnt(1)
	v_and_b32_e32 v47, 0xffff0000, v42
	v_lshlrev_b32_e32 v46, 16, v42
	s_waitcnt lgkmcnt(0)
	v_and_b32_e32 v49, 0xffff0000, v44
	v_lshlrev_b32_e32 v48, 16, v44
	v_pk_mul_f32 v[46:47], v[78:79], v[46:47]
	v_pk_mul_f32 v[48:49], v[58:59], v[48:49]
	v_and_b32_e32 v51, 0xffff0000, v43
	v_lshlrev_b32_e32 v50, 16, v43
	v_and_b32_e32 v43, 0xffff0000, v45
	v_lshlrev_b32_e32 v42, 16, v45
	v_pk_mul_f32 v[52:53], v[60:61], v[42:43]
	v_cvt_pk_bf16_f32 v42, v46, v47
	v_cvt_pk_bf16_f32 v44, v48, v49
	ds_read_b64_tr_b16 v[46:47], v102 offset:17472
	ds_read_b64_tr_b16 v[48:49], v102 offset:19648
	v_pk_mul_f32 v[50:51], v[80:81], v[50:51]
	v_cvt_pk_bf16_f32 v45, v52, v53
	v_cvt_pk_bf16_f32 v43, v50, v51
	s_waitcnt lgkmcnt(1)
	v_and_b32_e32 v51, 0xffff0000, v46
	v_lshlrev_b32_e32 v50, 16, v46
	s_waitcnt lgkmcnt(0)
	v_and_b32_e32 v53, 0xffff0000, v48
	v_lshlrev_b32_e32 v52, 16, v48
	v_pk_mul_f32 v[50:51], v[74:75], v[50:51]
	v_pk_mul_f32 v[52:53], v[70:71], v[52:53]
	v_and_b32_e32 v55, 0xffff0000, v47
	v_lshlrev_b32_e32 v54, 16, v47
	v_and_b32_e32 v47, 0xffff0000, v49
	v_lshlrev_b32_e32 v46, 16, v49
	v_pk_mul_f32 v[56:57], v[72:73], v[46:47]
	v_cvt_pk_bf16_f32 v46, v50, v51
	v_cvt_pk_bf16_f32 v48, v52, v53
	ds_read_b64_tr_b16 v[50:51], v102 offset:34880
	ds_read_b64_tr_b16 v[52:53], v102 offset:37056
	v_pk_mul_f32 v[54:55], v[76:77], v[54:55]
	v_cvt_pk_bf16_f32 v49, v56, v57
	v_cvt_pk_bf16_f32 v47, v54, v55
	s_waitcnt lgkmcnt(1)
	v_and_b32_e32 v55, 0xffff0000, v50
	v_lshlrev_b32_e32 v54, 16, v50
	s_waitcnt lgkmcnt(0)
	v_and_b32_e32 v57, 0xffff0000, v52
	v_lshlrev_b32_e32 v56, 16, v52
	v_pk_mul_f32 v[54:55], v[66:67], v[54:55]
	v_pk_mul_f32 v[56:57], v[62:63], v[56:57]
	v_and_b32_e32 v105, 0xffff0000, v51
	v_lshlrev_b32_e32 v104, 16, v51
	v_and_b32_e32 v51, 0xffff0000, v53
	v_lshlrev_b32_e32 v50, 16, v53
	v_pk_mul_f32 v[106:107], v[64:65], v[50:51]
	v_cvt_pk_bf16_f32 v50, v54, v55
	v_cvt_pk_bf16_f32 v52, v56, v57
	ds_read_b64_tr_b16 v[54:55], v102 offset:52288
	ds_read_b64_tr_b16 v[56:57], v102 offset:54464
	v_pk_mul_f32 v[104:105], v[68:69], v[104:105]
	v_cvt_pk_bf16_f32 v53, v106, v107
	v_cvt_pk_bf16_f32 v51, v104, v105
	s_waitcnt lgkmcnt(1)
	v_and_b32_e32 v105, 0xffff0000, v54
	v_lshlrev_b32_e32 v104, 16, v54
	s_waitcnt lgkmcnt(0)
	v_and_b32_e32 v107, 0xffff0000, v56
	v_lshlrev_b32_e32 v106, 16, v56
	v_pk_mul_f32 v[104:105], v[38:39], v[104:105]
	v_pk_mul_f32 v[106:107], v[34:35], v[106:107]
	v_and_b32_e32 v109, 0xffff0000, v55
	v_lshlrev_b32_e32 v108, 16, v55
	v_and_b32_e32 v55, 0xffff0000, v57
	v_lshlrev_b32_e32 v54, 16, v57
	v_pk_mul_f32 v[110:111], v[36:37], v[54:55]
	v_cvt_pk_bf16_f32 v54, v104, v105
	v_cvt_pk_bf16_f32 v56, v106, v107
	ds_read_b64_tr_b16 v[104:105], v102 offset:96
	ds_read_b64_tr_b16 v[106:107], v102 offset:2272
	v_pk_mul_f32 v[108:109], v[40:41], v[108:109]
	s_lshl_b32 s2, s26, 3
	v_cvt_pk_bf16_f32 v55, v108, v109
	s_waitcnt lgkmcnt(1)
	v_and_b32_e32 v109, 0xffff0000, v104
	v_lshlrev_b32_e32 v108, 16, v104
	v_pk_mul_f32 v[78:79], v[78:79], v[108:109]
	s_waitcnt lgkmcnt(0)
	v_and_b32_e32 v109, 0xffff0000, v106
	v_lshlrev_b32_e32 v108, 16, v106
	v_pk_mul_f32 v[108:109], v[58:59], v[108:109]
	v_and_b32_e32 v59, 0xffff0000, v105
	v_lshlrev_b32_e32 v58, 16, v105
	v_pk_mul_f32 v[80:81], v[80:81], v[58:59]
	v_and_b32_e32 v59, 0xffff0000, v107
	v_lshlrev_b32_e32 v58, 16, v107
	v_pk_mul_f32 v[104:105], v[60:61], v[58:59]
	v_cvt_pk_bf16_f32 v58, v78, v79
	v_cvt_pk_bf16_f32 v59, v80, v81
	ds_read_b64_tr_b16 v[78:79], v102 offset:17504
	ds_read_b64_tr_b16 v[80:81], v102 offset:19680
	v_cvt_pk_bf16_f32 v61, v104, v105
	s_add_i32 s2, s24, s2
	s_ashr_i32 s3, s2, 31
	s_waitcnt lgkmcnt(1)
	v_and_b32_e32 v105, 0xffff0000, v78
	v_lshlrev_b32_e32 v104, 16, v78
	v_pk_mul_f32 v[74:75], v[74:75], v[104:105]
	s_waitcnt lgkmcnt(0)
	v_and_b32_e32 v105, 0xffff0000, v80
	v_lshlrev_b32_e32 v104, 16, v80
	v_pk_mul_f32 v[104:105], v[70:71], v[104:105]
	v_and_b32_e32 v71, 0xffff0000, v79
	v_lshlrev_b32_e32 v70, 16, v79
	v_pk_mul_f32 v[76:77], v[76:77], v[70:71]
	v_and_b32_e32 v71, 0xffff0000, v81
	v_lshlrev_b32_e32 v70, 16, v81
	v_pk_mul_f32 v[78:79], v[72:73], v[70:71]
	v_cvt_pk_bf16_f32 v70, v74, v75
	v_cvt_pk_bf16_f32 v71, v76, v77
	ds_read_b64_tr_b16 v[74:75], v102 offset:34912
	ds_read_b64_tr_b16 v[76:77], v102 offset:37088
	v_cvt_pk_bf16_f32 v73, v78, v79
	s_lshl_b64 s[2:3], s[2:3], 14
	v_cvt_pk_bf16_f32 v57, v110, v111
	s_waitcnt lgkmcnt(1)
	v_and_b32_e32 v79, 0xffff0000, v74
	v_lshlrev_b32_e32 v78, 16, v74
	v_pk_mul_f32 v[66:67], v[66:67], v[78:79]
	s_waitcnt lgkmcnt(0)
	v_and_b32_e32 v79, 0xffff0000, v76
	v_lshlrev_b32_e32 v78, 16, v76
	v_pk_mul_f32 v[78:79], v[62:63], v[78:79]
	v_and_b32_e32 v63, 0xffff0000, v75
	v_lshlrev_b32_e32 v62, 16, v75
	v_pk_mul_f32 v[68:69], v[68:69], v[62:63]
	v_and_b32_e32 v63, 0xffff0000, v77
	v_lshlrev_b32_e32 v62, 16, v77
	v_pk_mul_f32 v[74:75], v[64:65], v[62:63]
	v_cvt_pk_bf16_f32 v62, v66, v67
	v_cvt_pk_bf16_f32 v63, v68, v69
	ds_read_b64_tr_b16 v[66:67], v102 offset:52320
	ds_read_b64_tr_b16 v[68:69], v102 offset:54496
	v_cvt_pk_bf16_f32 v65, v74, v75
	v_cvt_pk_bf16_f32 v60, v108, v109
	v_cvt_pk_bf16_f32 v72, v104, v105
	s_waitcnt lgkmcnt(1)
	v_and_b32_e32 v75, 0xffff0000, v66
	v_lshlrev_b32_e32 v74, 16, v66
	v_pk_mul_f32 v[38:39], v[38:39], v[74:75]
	s_waitcnt lgkmcnt(0)
	v_and_b32_e32 v75, 0xffff0000, v68
	v_lshlrev_b32_e32 v74, 16, v68
	v_pk_mul_f32 v[74:75], v[34:35], v[74:75]
	v_and_b32_e32 v35, 0xffff0000, v67
	v_lshlrev_b32_e32 v34, 16, v67
	v_pk_mul_f32 v[40:41], v[40:41], v[34:35]
	v_and_b32_e32 v35, 0xffff0000, v69
	v_lshlrev_b32_e32 v34, 16, v69
	v_pk_mul_f32 v[66:67], v[36:37], v[34:35]
	v_cvt_pk_bf16_f32 v64, v78, v79
	v_cvt_pk_bf16_f32 v34, v38, v39
	v_cvt_pk_bf16_f32 v35, v40, v41
	v_cvt_pk_bf16_f32 v36, v74, v75
	v_cvt_pk_bf16_f32 v37, v66, v67
	v_lshl_add_u64 v[38:39], v[84:85], 0, s[2:3]
	s_mov_b32 s2, 0
	v_bfe_u32 v116, v220, 4, 1
	v_mul_u32_u24_e32 v116, 24, v116
	v_add_u32_e32 v116, -32, v116
	v_mov_b32_e32 v117, -1
.LBB0_306:
	v_add_u32_e32 v40, s2, v8
	v_add_u32_e32 v41, 0x11000, v40
	ds_read_b64_tr_b16 v[66:67], v41
	v_add_u32_e32 v41, 0x11880, v40
	ds_read_b64_tr_b16 v[68:69], v41
	v_add_u32_e32 v41, 0x15400, v40
	ds_read_b64_tr_b16 v[108:109], v41
	v_add_u32_e32 v41, 0x15c80, v40
	ds_read_b64_tr_b16 v[110:111], v41
	v_add_u32_e32 v41, 0x19800, v40
	s_add_i32 s2, s2, 32
	s_waitcnt lgkmcnt(2)
	v_mfma_f32_16x16x32_bf16 v[74:77], v[66:69], v[0:3], 0
	v_mfma_f32_16x16x32_bf16 v[78:81], v[66:69], v[18:21], 0
	v_mfma_f32_16x16x32_bf16 v[104:107], v[66:69], v[42:45], 0
	v_mfma_f32_16x16x32_bf16 v[66:69], v[66:69], v[58:61], 0
	s_waitcnt lgkmcnt(0)
	v_mfma_f32_16x16x32_bf16 v[74:77], v[108:111], v[4:7], v[74:77]
	v_mfma_f32_16x16x32_bf16 v[78:81], v[108:111], v[22:25], v[78:81]
	v_mfma_f32_16x16x32_bf16 v[104:107], v[108:111], v[46:49], v[104:107]
	v_mfma_f32_16x16x32_bf16 v[66:69], v[108:111], v[70:73], v[66:69]
	ds_read_b64_tr_b16 v[108:109], v41
	v_add_u32_e32 v41, 0x1a080, v40
	ds_read_b64_tr_b16 v[110:111], v41
	v_add_u32_e32 v41, 0x1dc00, v40
	v_add_u32_e32 v40, 0x1e480, v40
	s_waitcnt lgkmcnt(0)
	v_mfma_f32_16x16x32_bf16 v[74:77], v[108:111], v[10:13], v[74:77]
	v_mfma_f32_16x16x32_bf16 v[78:81], v[108:111], v[26:29], v[78:81]
	v_mfma_f32_16x16x32_bf16 v[104:107], v[108:111], v[50:53], v[104:107]
	v_mfma_f32_16x16x32_bf16 v[66:69], v[108:111], v[62:65], v[66:69]
	ds_read_b64_tr_b16 v[108:109], v41
	ds_read_b64_tr_b16 v[110:111], v40
	s_waitcnt lgkmcnt(0)
	v_mfma_f32_16x16x32_bf16 v[74:77], v[108:111], v[14:17], v[74:77]
	s_nop 7
	v_cvt_pk_bf16_f32 v112, v74, v75
	v_mfma_f32_16x16x32_bf16 v[78:81], v[108:111], v[30:33], v[78:81]
	v_cvt_pk_bf16_f32 v113, v76, v77
	v_add_co_u32_e32 v74, vcc, s34, v38
	v_mfma_f32_16x16x32_bf16 v[104:107], v[108:111], v[54:57], v[104:107]
	s_nop 3
	v_cvt_pk_bf16_f32 v120, v78, v79
	v_cvt_pk_bf16_f32 v121, v80, v81
	v_mfma_f32_16x16x32_bf16 v[66:69], v[108:111], v[34:37], v[66:69]
	v_addc_co_u32_e32 v75, vcc, 0, v39, vcc
	v_cvt_pk_bf16_f32 v124, v104, v105
	v_cvt_pk_bf16_f32 v125, v106, v107
	s_nop 2
	v_cvt_pk_bf16_f32 v132, v66, v67
	v_add_co_u32_e32 v66, vcc, 0x3000, v38
	v_cvt_pk_bf16_f32 v133, v68, v69
	s_nop 0
	v_addc_co_u32_e32 v67, vcc, 0, v39, vcc
	v_lshl_add_u64 v[38:39], v[38:39], 0, 32
	v_add_u32_e32 v40, s2, v8
	v_add_u32_e32 v41, 0x11000, v40
	ds_read_b64_tr_b16 v[66:67], v41
	v_add_u32_e32 v41, 0x11880, v40
	ds_read_b64_tr_b16 v[68:69], v41
	v_add_u32_e32 v41, 0x15400, v40
	ds_read_b64_tr_b16 v[108:109], v41
	v_add_u32_e32 v41, 0x15c80, v40
	ds_read_b64_tr_b16 v[110:111], v41
	v_add_u32_e32 v41, 0x19800, v40
	s_add_i32 s2, s2, 32
	s_cmpk_lg_i32 s2, 0x100
	s_waitcnt lgkmcnt(2)
	v_mfma_f32_16x16x32_bf16 v[74:77], v[66:69], v[0:3], 0
	v_mfma_f32_16x16x32_bf16 v[78:81], v[66:69], v[18:21], 0
	v_mfma_f32_16x16x32_bf16 v[104:107], v[66:69], v[42:45], 0
	v_mfma_f32_16x16x32_bf16 v[66:69], v[66:69], v[58:61], 0
	s_waitcnt lgkmcnt(0)
	v_mfma_f32_16x16x32_bf16 v[74:77], v[108:111], v[4:7], v[74:77]
	v_mfma_f32_16x16x32_bf16 v[78:81], v[108:111], v[22:25], v[78:81]
	v_mfma_f32_16x16x32_bf16 v[104:107], v[108:111], v[46:49], v[104:107]
	v_mfma_f32_16x16x32_bf16 v[66:69], v[108:111], v[70:73], v[66:69]
	ds_read_b64_tr_b16 v[108:109], v41
	v_add_u32_e32 v41, 0x1a080, v40
	ds_read_b64_tr_b16 v[110:111], v41
	v_add_u32_e32 v41, 0x1dc00, v40
	v_add_u32_e32 v40, 0x1e480, v40
	s_waitcnt lgkmcnt(0)
	v_mfma_f32_16x16x32_bf16 v[74:77], v[108:111], v[10:13], v[74:77]
	v_mfma_f32_16x16x32_bf16 v[78:81], v[108:111], v[26:29], v[78:81]
	v_mfma_f32_16x16x32_bf16 v[104:107], v[108:111], v[50:53], v[104:107]
	v_mfma_f32_16x16x32_bf16 v[66:69], v[108:111], v[62:65], v[66:69]
	ds_read_b64_tr_b16 v[108:109], v41
	ds_read_b64_tr_b16 v[110:111], v40
	s_waitcnt lgkmcnt(0)
	v_mfma_f32_16x16x32_bf16 v[74:77], v[108:111], v[14:17], v[74:77]
	s_nop 7
	v_cvt_pk_bf16_f32 v114, v74, v75
	v_mfma_f32_16x16x32_bf16 v[78:81], v[108:111], v[30:33], v[78:81]
	v_cvt_pk_bf16_f32 v115, v76, v77
	v_add_co_u32_e32 v74, vcc, s34, v38
	v_mfma_f32_16x16x32_bf16 v[104:107], v[108:111], v[54:57], v[104:107]
	v_lshl_add_u64 v[156:157], v[38:39], 0, v[116:117]
	v_add_co_u32_e32 v158, vcc, 0x3000, v156
	s_nop 1
	v_addc_co_u32_e32 v159, vcc, 0, v157, vcc
	v_add_co_u32_e32 v156, vcc, 0x1000, v156
	s_nop 1
	v_addc_co_u32_e32 v157, vcc, 0, v157, vcc
	v_permlane16_swap_b32_e32 v112, v114
	v_permlane16_swap_b32_e32 v113, v115
	global_store_dwordx4 v[156:157], v[112:115], off offset:-4096
	s_nop 3
	v_cvt_pk_bf16_f32 v122, v78, v79
	v_cvt_pk_bf16_f32 v123, v80, v81
	v_mfma_f32_16x16x32_bf16 v[66:69], v[108:111], v[34:37], v[66:69]
	v_addc_co_u32_e32 v75, vcc, 0, v39, vcc
	s_nop 1
	v_permlane16_swap_b32_e32 v120, v122
	v_permlane16_swap_b32_e32 v121, v123
	global_store_dwordx4 v[156:157], v[120:123], off
	v_cvt_pk_bf16_f32 v126, v104, v105
	v_cvt_pk_bf16_f32 v127, v106, v107
	s_nop 1
	v_permlane16_swap_b32_e32 v124, v126
	v_permlane16_swap_b32_e32 v125, v127
	global_store_dwordx4 v[158:159], v[124:127], off offset:-4096
	s_nop 2
	v_cvt_pk_bf16_f32 v134, v66, v67
	v_add_co_u32_e32 v66, vcc, 0x3000, v38
	v_cvt_pk_bf16_f32 v135, v68, v69
	s_nop 0
	v_addc_co_u32_e32 v67, vcc, 0, v39, vcc
	v_lshl_add_u64 v[38:39], v[38:39], 0, 32
	s_nop 1
	v_permlane16_swap_b32_e32 v132, v134
	v_permlane16_swap_b32_e32 v133, v135
	global_store_dwordx4 v[158:159], v[132:135], off
	s_cbranch_scc1 .LBB0_306
	s_add_i32 s26, s25, s26
	s_cmpk_gt_i32 s26, 0x10f
	s_barrier
	s_cbranch_scc0 .LBB0_292
